# FoX attention K tile: swizzle on 4 row bits (conflict-free ds_read_b128 for K, was 2-way), second address VGPR for d-chunks 4..7
# baseline (speedup 1.0000x reference)
.LBB0_555:
	v_writelane_b32 v255, s81, 16
	v_writelane_b32 v255, s66, 17
	v_writelane_b32 v255, s67, 18
	v_writelane_b32 v255, s65, 19
	v_writelane_b32 v255, s84, 20
	s_cmp_lg_u32 s12, 0
	s_nop 0
	v_writelane_b32 v255, s85, 21
	v_writelane_b32 v255, s82, 22
	s_nop 1
	v_writelane_b32 v255, s83, 23
	v_writelane_b32 v255, s78, 24
	s_nop 1
	v_writelane_b32 v255, s79, 25
	v_writelane_b32 v255, s76, 26
	s_nop 1
	v_writelane_b32 v255, s77, 27
	v_writelane_b32 v255, s74, 28
	s_nop 1
	v_writelane_b32 v255, s75, 29
	v_writelane_b32 v255, s86, 30
	v_writelane_b32 v255, s12, 31
	v_writelane_b32 v255, s89, 32
	s_cbranch_scc0 .LBB0_739
	s_and_b32 s0, s68, 7
	s_xor_b32 s1, s0, 7
	s_mov_b32 s2, s68
	s_cmpk_lt_i32 s68, 0x100
	v_writelane_b32 v255, s2, 33
	s_cselect_b32 s1, s0, s1
	s_ashr_i32 s0, s68, 3
	v_writelane_b32 v255, s3, 34
	s_ashr_i32 s5, s68, 7
	s_and_b32 s4, s0, 15
	v_readlane_b32 s2, v255, 24
	v_readlane_b32 s3, v255, 25
	s_add_u32 s84, s2, 0x10000
	s_addc_u32 s85, s3, 0
	s_lshl_b32 s2, s0, 2
	s_ashr_i32 s3, s2, 31
	s_lshl_b64 s[2:3], s[2:3], 2
	s_add_u32 s2, s84, s2
	s_addc_u32 s3, s85, s3
	v_mov_b32_e32 v2, 0
	v_readlane_b32 s10, v255, 2
	global_load_dwordx4 v[16:19], v2, s[2:3]
	v_readlane_b32 s11, v255, 3
	s_add_u32 s80, s10, 0x28100000
	s_mul_i32 s2, s5, 0x60
	s_addc_u32 s81, s11, 0
	s_or_b32 s2, s2, s4
	s_ashr_i32 s3, s2, 31
	s_lshl_b64 s[6:7], s[2:3], 20
	s_add_u32 s3, s80, s6
	s_addc_u32 s6, s81, s7
	s_lshl_b32 s7, s1, 16
	s_add_u32 s8, s3, s7
	s_addc_u32 s9, s6, 0
	s_or_b32 s6, s2, 16
	s_ashr_i32 s7, s6, 31
	s_lshl_b64 s[6:7], s[6:7], 20
	s_add_u32 s94, s80, s6
	s_addc_u32 s95, s81, s7
	s_add_i32 s2, s2, 32
	s_ashr_i32 s3, s2, 31
	s_lshl_b64 s[2:3], s[2:3], 20
	s_add_u32 s96, s80, s2
	s_addc_u32 s97, s81, s3
	s_lshl_b32 s83, s1, 8
	s_add_u32 s87, s10, 0x45a10000
	v_readlane_b32 s1, v255, 16
	s_addc_u32 s91, s11, 0
	s_bfe_u32 s6, s1, 0x30006
	v_mbcnt_lo_u32_b32 v3, -1, 0
	v_mbcnt_hi_u32_b32 v3, -1, v3
	s_lshl_b32 s7, s6, 12
	v_lshlrev_b32_e32 v0, 7, v3
	v_and_b32_e32 v0, 0xf80, v0
	v_or_b32_e32 v0, s7, v0
	v_lshlrev_b32_e32 v0, 1, v0
	s_waitcnt lgkmcnt(0)
	v_mov_b32_e32 v1, v2
	v_lshrrev_b32_e32 v4, 1, v3
	v_lshl_add_u64 v[0:1], s[8:9], 0, v[0:1]
	v_and_b32_e32 v4, 16, v4
	v_mov_b32_e32 v5, v2
	v_lshl_add_u64 v[0:1], v[0:1], 0, v[4:5]
	v_and_b32_e32 v28, 63, v3
	s_lshl_b32 s86, s6, 6
	global_load_dwordx4 v[156:159], v[0:1], off
	global_load_dwordx4 v[152:155], v[0:1], off offset:32
	global_load_dwordx4 v[148:151], v[0:1], off offset:64
	global_load_dwordx4 v[144:147], v[0:1], off offset:96
	global_load_dwordx4 v[8:11], v[0:1], off offset:128
	global_load_dwordx4 v[12:15], v[0:1], off offset:160
	global_load_dwordx4 v[80:83], v[0:1], off offset:192
	global_load_dwordx4 v[4:7], v[0:1], off offset:224
	v_or_b32_e32 v29, s86, v28
	v_lshrrev_b32_e32 v30, 4, v29
	v_or_b32_e32 v1, s83, v30
	v_lshlrev_b32_e32 v24, 8, v1
	v_lshlrev_b32_e32 v3, 4, v3
	v_or_b32_e32 v20, 0xc000, v24
	v_mov_b32_e32 v21, v2
	v_and_b32_e32 v0, 0xf0, v3
	v_lshl_add_u64 v[22:23], s[96:97], 0, v[20:21]
	v_mov_b32_e32 v1, v2
	v_or_b32_e32 v24, 0xe000, v24
	v_mov_b32_e32 v25, v2
	v_lshl_add_u64 v[20:21], s[94:95], 0, v[20:21]
	v_lshl_add_u64 v[26:27], s[96:97], 0, v[24:25]
	v_lshl_add_u64 v[20:21], v[20:21], 0, v[0:1]
	v_lshl_add_u64 v[24:25], s[94:95], 0, v[24:25]
	v_lshl_add_u64 v[22:23], v[22:23], 0, v[0:1]
	v_lshl_add_u64 v[26:27], v[26:27], 0, v[0:1]
	v_lshl_add_u64 v[0:1], v[24:25], 0, v[0:1]
	global_load_dwordx4 v[112:115], v[20:21], off
	global_load_dwordx4 v[116:119], v[0:1], off
	global_load_dwordx4 v[164:167], v[22:23], off
	global_load_dwordx4 v[168:171], v[26:27], off
	s_movk_i32 s1, 0xf0
	v_mov_b32_e32 v0, s86
	s_movk_i32 s2, 0xf0
	v_bitop3_b32 v1, v28, s1, v0 bitop3:0xc8
	s_waitcnt vmcnt(0)
	s_add_i32 s3, s83, 0x100
	v_lshlrev_b32_e32 v0, 2, v29
	v_lshlrev_b32_e32 v20, 8, v30
	v_bitop3_b32 v1, v3, v1, s2 bitop3:0x6c
	s_mov_b32 s70, 0
	v_add3_u32 v1, 0, v20, v1
	v_cmp_gt_u32_e32 vcc, s3, v0
	s_waitcnt vmcnt(3)
	ds_write_b128 v1, v[112:115] offset:32768
	s_waitcnt vmcnt(2)
	ds_write_b128 v1, v[116:119] offset:40960
	s_and_saveexec_b64 s[2:3], vcc
	s_cbranch_execz .LBB0_558
	s_ashr_i32 s1, s0, 31
	s_lshl_b64 s[0:1], s[0:1], 14
	s_add_u32 s0, s87, s0
	s_addc_u32 s1, s91, s1
	v_lshlrev_b32_e32 v0, 2, v0
	global_load_dwordx4 v[20:23], v0, s[0:1]
	v_add_u32_e32 v0, 0, v0
	v_add_u32_e32 v0, 0x10800, v0
	s_waitcnt vmcnt(0)
	ds_write_b128 v0, v[20:23]

.LBB0_566:
	v_lshrrev_b32_e32 v191, 5, v36
	v_lshlrev_b32_e32 v39, 2, v191
	v_lshl_add_u32 v199, v190, 2, s5
	v_sub_u32_e32 v196, v0, v39
	v_lshlrev_b32_e32 v1, 4, v190
	v_lshlrev_b32_e32 v174, 4, v191
	v_and_b32_e32 v1, 0xf0, v1
	v_lshlrev_b32_e32 v0, 8, v190
	v_xad_u32 v3, v174, v1, 0
	v_add_u32_e32 v202, v3, v0
	v_xor_b32_e32 v252, 0x80, v202
	ds_read_b128 v[4:7], v202 offset:32768
	ds_read_b128 v[40:43], v252 offset:32768
	v_or_b32_e32 v3, 32, v174
	s_waitcnt lgkmcnt(1)
	v_mfma_f32_32x32x16_bf16 v[20:35], v[4:7], v[156:159], 0
	ds_read_b128 v[4:7], v202 offset:40960
	ds_read_b128 v[44:47], v252 offset:40960
	v_xad_u32 v3, v3, v1, 0
	v_add_u32_e32 v203, v3, v0
	v_xor_b32_e32 v253, 0x80, v203
	ds_read_b128 v[48:51], v203 offset:32768
	ds_read_b128 v[52:55], v253 offset:32768
	v_or_b32_e32 v3, 64, v174
	v_xad_u32 v3, v3, v1, 0
	s_waitcnt lgkmcnt(1)
	v_mfma_f32_32x32x16_bf16 v[20:35], v[48:51], v[152:155], v[20:35]
	ds_read_b128 v[48:51], v203 offset:40960
	ds_read_b128 v[56:59], v253 offset:40960
	v_add_u32_e32 v204, v3, v0
	v_xor_b32_e32 v254, 0x80, v204
	v_or_b32_e32 v3, 0x60, v174
	v_xad_u32 v1, v3, v1, 0
	v_add_u32_e32 v205, v1, v0
	v_xor_b32_e32 v176, 0x80, v205
	v_lshl_add_u32 v0, s4, 8, v199
	v_mfma_f32_32x32x16_bf16 v[4:19], v[4:7], v[156:159], 0
	v_cmp_gt_u32_e64 s[2:3], 32, v36
	s_mov_b64 vcc, s[2:3]
	s_lshl_b32 s4, s4, 6
	s_or_b32 s5, s4, 63
	s_cmp_le_u32 s5, s93
	s_waitcnt lgkmcnt(1)
	v_mfma_f32_32x32x16_bf16 v[4:19], v[48:51], v[152:155], v[4:19]
	ds_read_b128 v[48:51], v204 offset:32768
	ds_read_b128 v[60:63], v254 offset:32768
	ds_read_b128 v[64:67], v254 offset:40960
	s_waitcnt lgkmcnt(2)
	v_mfma_f32_32x32x16_bf16 v[20:35], v[48:51], v[148:151], v[20:35]
	ds_read_b128 v[48:51], v204 offset:40960
	s_waitcnt lgkmcnt(0)
	v_mfma_f32_32x32x16_bf16 v[4:19], v[48:51], v[148:151], v[4:19]
	ds_read_b128 v[48:51], v205 offset:32768
	ds_read_b128 v[68:71], v176 offset:32768
	s_waitcnt lgkmcnt(1)
	v_mfma_f32_32x32x16_bf16 v[20:35], v[48:51], v[144:147], v[20:35]
	ds_read_b128 v[48:51], v205 offset:40960
	ds_read_b128 v[72:75], v176 offset:40960
	s_waitcnt lgkmcnt(1)
	v_mfma_f32_32x32x16_bf16 v[4:19], v[48:51], v[144:147], v[4:19]
	ds_read_b128 v[48:51], v175
	ds_read_b128 v[76:79], v175 offset:1024
	s_waitcnt lgkmcnt(1)
	v_mfma_f32_32x32x16_bf16 v[20:35], v[40:43], v[48:51], v[20:35]
	v_mfma_f32_32x32x16_bf16 v[4:19], v[44:47], v[48:51], v[4:19]
	ds_read_b128 v[40:43], v175 offset:2048
	ds_read_b128 v[44:47], v175 offset:3072
	ds_read2_b32 v[0:1], v0 offset1:32
	s_waitcnt lgkmcnt(0)
	v_and_b32_e32 v3, 0xffff0000, v0
	v_mfma_f32_32x32x16_bf16 v[20:35], v[52:55], v[76:79], v[20:35]
	v_sub_f32_e32 v3, v0, v3
	v_mfma_f32_32x32x16_bf16 v[4:19], v[56:59], v[76:79], v[4:19]
	v_mfma_f32_32x32x16_bf16 v[20:35], v[60:63], v[40:43], v[20:35]
	v_mfma_f32_32x32x16_bf16 v[4:19], v[64:67], v[40:43], v[4:19]
	v_and_b32_e32 v41, 0xffff0000, v1
	v_sub_f32_e32 v41, v1, v41
	v_and_b32_e32 v40, 0xffff0000, v3
	v_and_b32_e32 v42, 0xffff0000, v41
	v_or_b32_sdwa v0, v40, v0 dst_sel:DWORD dst_unused:UNUSED_PAD src0_sel:DWORD src1_sel:WORD_1
	v_sub_f32_e32 v3, v3, v40
	v_or_b32_sdwa v1, v42, v1 dst_sel:DWORD dst_unused:UNUSED_PAD src0_sel:DWORD src1_sel:WORD_1
	v_mfma_f32_32x32x16_bf16 v[20:35], v[68:71], v[44:47], v[20:35]
	v_sub_f32_e32 v41, v41, v42
	v_cndmask_b32_e64 v40, 0, v1, s[2:3]
	v_cndmask_b32_sdwa v1, v2, v3, vcc dst_sel:DWORD dst_unused:UNUSED_PAD src0_sel:DWORD src1_sel:WORD_1
	v_cndmask_b32_e64 v0, 0, v0, s[2:3]
	v_mov_b32_e32 v3, v2
	v_cndmask_b32_sdwa v41, v2, v41, vcc dst_sel:DWORD dst_unused:UNUSED_PAD src0_sel:DWORD src1_sel:WORD_1
	v_mov_b32_e32 v42, v2
	v_mfma_f32_32x32x16_bf16 v[4:19], v[72:75], v[44:47], v[4:19]
	v_mov_b32_e32 v43, v2
	v_mov_b64_e32 v[44:45], s[68:69]
	v_mov_b64_e32 v[46:47], s[70:71]
	s_nop 1
	v_mfma_f32_32x32x16_bf16 v[20:35], v[0:3], v[44:47], v[20:35]
	v_mfma_f32_32x32x16_bf16 v[4:19], v[40:43], v[44:47], v[4:19]
	s_cbranch_scc1 .LBB0_568
	v_subrev_u32_e32 v0, s4, v196
	v_cmp_gt_i32_e64 s[62:63], 26, v0
	v_cmp_gt_i32_e64 s[64:65], 27, v0
	v_cmp_gt_i32_e64 s[60:61], 25, v0
	s_and_b64 s[62:63], s[64:65], s[62:63]
	v_cmp_gt_i32_e64 s[58:59], 24, v0
	s_and_b64 s[60:61], s[62:63], s[60:61]
	v_cmp_gt_i32_e64 s[56:57], 19, v0
	s_and_b64 s[58:59], s[60:61], s[58:59]
	v_cmp_gt_i32_e64 s[54:55], 18, v0
	s_and_b64 s[56:57], s[58:59], s[56:57]
	v_cmp_gt_i32_e64 s[52:53], 17, v0
	s_and_b64 s[54:55], s[56:57], s[54:55]
	v_cmp_gt_i32_e64 s[50:51], 16, v0
	s_and_b64 s[52:53], s[54:55], s[52:53]
	v_cmp_gt_i32_e64 s[48:49], 11, v0
	s_and_b64 s[50:51], s[52:53], s[50:51]
	v_cmp_gt_i32_e64 s[46:47], 10, v0
	s_and_b64 s[48:49], s[50:51], s[48:49]
	v_cmp_gt_i32_e64 s[44:45], 9, v0
	s_and_b64 s[46:47], s[48:49], s[46:47]
	v_cmp_gt_i32_e64 s[42:43], 8, v0
	s_and_b64 s[44:45], s[46:47], s[44:45]
	v_cmp_gt_i32_e64 s[40:41], 3, v0
	s_and_b64 s[42:43], s[44:45], s[42:43]
	v_cmp_gt_i32_e64 s[38:39], 2, v0
	s_and_b64 s[40:41], s[42:43], s[40:41]
	v_cmp_gt_i32_e64 s[36:37], 1, v0
	s_and_b64 s[38:39], s[40:41], s[38:39]
	v_cmp_gt_i32_e64 s[34:35], 0, v0
	s_and_b64 s[36:37], s[38:39], s[36:37]
	s_and_b64 s[34:35], s[36:37], s[34:35]
	v_cmp_gt_i32_e64 s[30:31], 58, v0
	v_cndmask_b32_e64 v20, v20, v186, s[34:35]
	v_cmp_gt_i32_e64 s[34:35], 59, v0
	v_cmp_gt_i32_e64 s[28:29], 57, v0
	s_and_b64 s[30:31], s[34:35], s[30:31]
	v_cmp_gt_i32_e64 s[26:27], 56, v0
	s_and_b64 s[28:29], s[30:31], s[28:29]
	v_cmp_gt_i32_e64 s[24:25], 51, v0
	s_and_b64 s[26:27], s[28:29], s[26:27]
	v_cmp_gt_i32_e64 s[22:23], 50, v0
	s_and_b64 s[24:25], s[26:27], s[24:25]
	v_cmp_gt_i32_e64 s[20:21], 49, v0
	s_and_b64 s[22:23], s[24:25], s[22:23]
	v_cmp_gt_i32_e64 s[18:19], 48, v0
	s_and_b64 s[20:21], s[22:23], s[20:21]
	v_cmp_gt_i32_e64 s[16:17], 43, v0
	s_and_b64 s[18:19], s[20:21], s[18:19]
	v_cmp_gt_i32_e64 s[14:15], 42, v0
	s_and_b64 s[16:17], s[18:19], s[16:17]
	v_cmp_gt_i32_e64 s[12:13], 41, v0
	s_and_b64 s[14:15], s[16:17], s[14:15]
	v_cmp_gt_i32_e64 s[10:11], 40, v0
	s_and_b64 s[12:13], s[14:15], s[12:13]
	v_cmp_gt_i32_e64 s[8:9], 35, v0
	s_and_b64 s[10:11], s[12:13], s[10:11]
	v_cmp_gt_i32_e64 s[6:7], 34, v0
	s_and_b64 s[8:9], s[10:11], s[8:9]
	v_cmp_gt_i32_e64 s[4:5], 33, v0
	s_and_b64 s[6:7], s[8:9], s[6:7]
	v_cmp_gt_i32_e32 vcc, 32, v0
	s_and_b64 s[4:5], s[6:7], s[4:5]
	s_and_b64 vcc, s[4:5], vcc
	v_cndmask_b32_e64 v35, v35, v186, s[64:65]
	v_cndmask_b32_e64 v34, v34, v186, s[62:63]
	v_cndmask_b32_e64 v33, v33, v186, s[60:61]
	v_cndmask_b32_e64 v32, v32, v186, s[58:59]
	v_cndmask_b32_e64 v31, v31, v186, s[56:57]
	v_cndmask_b32_e64 v30, v30, v186, s[54:55]
	v_cndmask_b32_e64 v29, v29, v186, s[52:53]
	v_cndmask_b32_e64 v28, v28, v186, s[50:51]
	v_cndmask_b32_e64 v27, v27, v186, s[48:49]
	v_cndmask_b32_e64 v26, v26, v186, s[46:47]
	v_cndmask_b32_e64 v25, v25, v186, s[44:45]
	v_cndmask_b32_e64 v24, v24, v186, s[42:43]
	v_cndmask_b32_e64 v23, v23, v186, s[40:41]
	v_cndmask_b32_e64 v22, v22, v186, s[38:39]
	v_cndmask_b32_e64 v21, v21, v186, s[36:37]
	v_cndmask_b32_e64 v19, v19, v186, s[34:35]
	v_cndmask_b32_e64 v18, v18, v186, s[30:31]
	v_cndmask_b32_e64 v17, v17, v186, s[28:29]
	v_cndmask_b32_e64 v16, v16, v186, s[26:27]
	v_cndmask_b32_e64 v15, v15, v186, s[24:25]
	v_cndmask_b32_e64 v14, v14, v186, s[22:23]
	v_cndmask_b32_e64 v13, v13, v186, s[20:21]
	v_cndmask_b32_e64 v12, v12, v186, s[18:19]
	v_cndmask_b32_e64 v11, v11, v186, s[16:17]
	v_cndmask_b32_e64 v10, v10, v186, s[14:15]
	v_cndmask_b32_e64 v9, v9, v186, s[12:13]
	v_cndmask_b32_e64 v8, v8, v186, s[10:11]
	v_cndmask_b32_e64 v7, v7, v186, s[8:9]
	v_cndmask_b32_e64 v6, v6, v186, s[6:7]
	v_cndmask_b32_e64 v5, v5, v186, s[4:5]
	v_cndmask_b32_e32 v4, v4, v186, vcc
.LBB0_568:
	v_lshlrev_b32_e32 v0, 8, v197
	v_and_b32_e32 v1, 0xf0, v192
	v_bitop3_b32 v1, v172, v0, v1 bitop3:0xde
	s_nop 7
	v_max_f32_e32 v0, v4, v4
	v_max_f32_e32 v3, v20, v20
	v_max_f32_e32 v0, v3, v0
	v_max3_f32 v0, v0, v21, v5
	v_max3_f32 v0, v0, v22, v6
	v_max3_f32 v0, v0, v23, v7
	v_max3_f32 v0, v0, v24, v8
	v_max3_f32 v0, v0, v25, v9
	v_max3_f32 v0, v0, v26, v10
	v_max3_f32 v0, v0, v27, v11
	v_max3_f32 v0, v0, v28, v12
	v_max3_f32 v0, v0, v29, v13
	v_max3_f32 v0, v0, v30, v14
	v_max3_f32 v0, v0, v31, v15
	v_max3_f32 v0, v0, v32, v16
	v_max3_f32 v0, v0, v33, v17
	v_max3_f32 v0, v0, v34, v18
	v_max3_f32 v0, v0, v35, v19
	v_mov_b32_e32 v3, v0
	s_nop 1
	v_permlane32_swap_b32_e32 v0, v3
	v_max_f32_e32 v3, v3, v3
	v_max_f32_e32 v0, v0, v0
	v_max_f32_e32 v0, v0, v3
	v_add_f32_e32 v3, 0x7149f2ca, v0
	v_mul_f32_e32 v3, 0x3db504f3, v3
	v_cmp_ge_f32_e32 vcc, s67, v3
	s_cmp_eq_u64 vcc, exec
	s_cselect_b64 s[4:5], -1, 0
	s_andn2_b64 vcc, exec, s[0:1]
	v_add_u32_e32 v193, 0, v1
	s_cbranch_vccnz .LBB0_570
	s_waitcnt vmcnt(0)
	s_waitcnt vmcnt(1)
	ds_write_b128 v193, v[112:115] offset:49152
	s_waitcnt vmcnt(0)
	ds_write_b128 v193, v[116:119] offset:57344

.LBB0_574:
	v_add_u32_e32 v80, s94, v209
	v_add_u32_e32 v0, 0xffffff81, v80
	v_add_u32_e32 v6, 0xffffffa1, v80
	v_ashrrev_i32_e32 v1, 31, v0
	v_ashrrev_i32_e32 v7, 31, v6
	v_lshlrev_b64 v[0:1], 8, v[0:1]
	v_lshlrev_b64 v[6:7], 8, v[6:7]
	s_waitcnt vmcnt(3)
	ds_write_b128 v200, v[164:167] offset:16384
	s_waitcnt vmcnt(2)
	ds_write_b128 v201, v[168:171] offset:16384
	v_lshl_add_u64 v[4:5], v[12:13], 0, v[0:1]
	v_lshl_add_u64 v[8:9], v[12:13], 0, v[6:7]
	global_load_dwordx4 v[164:167], v[4:5], off
	global_load_dwordx4 v[168:171], v[8:9], off
	v_lshl_add_u64 v[0:1], v[14:15], 0, v[0:1]
	v_lshl_add_u64 v[8:9], v[14:15], 0, v[6:7]
	global_load_dwordx4 v[4:7], v[0:1], off
	s_nop 0
	global_load_dwordx4 v[8:11], v[8:9], off
	ds_read2_b32 v[212:213], v211 offset0:64 offset1:96
	ds_read_b128 v[82:85], v202 offset:49152
	ds_read_b128 v[86:89], v202 offset:57344
	s_waitcnt vmcnt(4)
	ds_read_b128 v[116:119], v203 offset:49152
	ds_read_b128 v[224:227], v203 offset:57344
	v_exp_f32_e32 v128, v128
	s_waitcnt lgkmcnt(4)
	v_and_b32_e32 v0, 0xffff0000, v212
	s_waitcnt lgkmcnt(3)
	v_mfma_f32_32x32x16_bf16 v[100:115], v[82:85], v[156:159], 0
	v_sub_f32_e32 v0, v212, v0
	v_and_b32_e32 v3, 0xffff0000, v213
	v_and_b32_e32 v1, 0xffff0000, v0
	v_sub_f32_e32 v3, v213, v3
	v_and_b32_e32 v81, 0xffff0000, v3
	v_sub_f32_e32 v0, v0, v1
	v_sub_f32_e32 v3, v3, v81
	s_waitcnt lgkmcnt(2)
	v_mfma_f32_32x32x16_bf16 v[84:99], v[86:89], v[156:159], 0
	v_lshrrev_b32_e32 v0, 16, v0
	v_or_b32_sdwa v82, v1, v212 dst_sel:DWORD dst_unused:UNUSED_PAD src0_sel:DWORD src1_sel:WORD_1
	v_cndmask_b32_e64 v1, 0, v0, s[2:3]
	v_or_b32_sdwa v0, v81, v213 dst_sel:DWORD dst_unused:UNUSED_PAD src0_sel:DWORD src1_sel:WORD_1
	v_lshrrev_b32_e32 v3, 16, v3
	v_exp_f32_e32 v81, v133
	v_exp_f32_e32 v83, v131
	s_waitcnt lgkmcnt(0)
	v_mfma_f32_32x32x16_bf16 v[84:99], v[224:227], v[152:155], v[84:99]
	v_exp_f32_e32 v129, v129
	v_exp_f32_e32 v131, v121
	v_exp_f32_e32 v133, v123
	v_exp_f32_e32 v214, v126
	v_exp_f32_e32 v223, v127
	v_mfma_f32_32x32x16_bf16 v[100:115], v[116:119], v[152:155], v[100:115]
	ds_read_b128 v[116:119], v204 offset:49152
	ds_read_b128 v[224:227], v204 offset:57344
	s_waitcnt lgkmcnt(0)
	v_mfma_f32_32x32x16_bf16 v[84:99], v[224:227], v[148:151], v[84:99]
	v_mfma_f32_32x32x16_bf16 v[100:115], v[116:119], v[148:151], v[100:115]
	ds_read_b128 v[116:119], v205 offset:49152
	ds_read_b128 v[224:227], v205 offset:57344
	s_waitcnt lgkmcnt(0)
	v_mfma_f32_32x32x16_bf16 v[84:99], v[224:227], v[144:147], v[84:99]
	v_mfma_f32_32x32x16_bf16 v[100:115], v[116:119], v[144:147], v[100:115]
	ds_read_b128 v[116:119], v252 offset:49152
	ds_read_b128 v[224:227], v252 offset:57344
	ds_read_b128 v[228:231], v175
	s_waitcnt lgkmcnt(0)
	v_mfma_f32_32x32x16_bf16 v[84:99], v[224:227], v[228:231], v[84:99]
	v_mfma_f32_32x32x16_bf16 v[100:115], v[116:119], v[228:231], v[100:115]
	ds_read_b128 v[116:119], v253 offset:49152
	ds_read_b128 v[224:227], v253 offset:57344
	ds_read_b128 v[228:231], v175 offset:1024
	s_waitcnt lgkmcnt(0)
	v_mfma_f32_32x32x16_bf16 v[84:99], v[224:227], v[228:231], v[84:99]
	v_mfma_f32_32x32x16_bf16 v[100:115], v[116:119], v[228:231], v[100:115]
	ds_read_b128 v[116:119], v254 offset:49152
	ds_read_b128 v[224:227], v254 offset:57344
	ds_read_b128 v[228:231], v175 offset:2048
	s_waitcnt lgkmcnt(0)
	v_mfma_f32_32x32x16_bf16 v[84:99], v[224:227], v[228:231], v[84:99]
	v_mfma_f32_32x32x16_bf16 v[100:115], v[116:119], v[228:231], v[100:115]
	ds_read_b128 v[116:119], v176 offset:49152
	ds_read_b128 v[224:227], v176 offset:57344
	ds_read_b128 v[228:231], v175 offset:3072
	s_waitcnt lgkmcnt(0)
	v_mfma_f32_32x32x16_bf16 v[84:99], v[224:227], v[228:231], v[84:99]
	v_mov_b64_e32 v[226:227], s[70:71]
	v_mov_b64_e32 v[224:225], s[68:69]
	v_mfma_f32_32x32x16_bf16 v[100:115], v[116:119], v[228:231], v[100:115]
	v_cndmask_b32_e64 v116, 0, v0, s[2:3]
	v_cndmask_b32_e64 v117, 0, v3, s[2:3]
	v_mov_b32_e32 v118, v2
	v_mov_b32_e32 v119, v2
	v_cndmask_b32_e64 v0, 0, v82, s[2:3]
	v_mov_b32_e32 v3, v2
	v_exp_f32_e32 v82, v130
	v_mfma_f32_32x32x16_bf16 v[84:99], v[116:119], v[224:227], v[84:99]
	v_add_f32_e32 v116, 0, v220
	v_add_f32_e32 v116, v222, v116
	v_add_f32_e32 v116, v218, v116
	v_add_f32_e32 v116, v221, v116
	v_add_f32_e32 v116, v217, v116
	v_add_f32_e32 v116, v219, v116
	v_add_f32_e32 v116, v215, v116
	v_add_f32_e32 v116, v216, v116
	v_add_f32_e32 v116, v140, v116
	v_add_f32_e32 v116, v143, v116
	v_add_f32_e32 v116, v138, v116
	v_add_f32_e32 v116, v141, v116
	v_mfma_f32_32x32x16_bf16 v[100:115], v[0:3], v[224:227], v[100:115]
	v_exp_f32_e32 v0, v134
	v_add_f32_e32 v116, v136, v116
	v_exp_f32_e32 v1, v135
	v_add_f32_e32 v116, v142, v116
	v_exp_f32_e32 v3, v132
	v_add_f32_e32 v116, v137, v116
	v_add_f32_e32 v116, v139, v116
	v_add_f32_e32 v116, v0, v116
	v_add_f32_e32 v116, v1, v116
	v_add_f32_e32 v116, v3, v116
	v_add_f32_e32 v116, v81, v116
	v_exp_f32_e32 v130, v120
	v_add_f32_e32 v116, v82, v116
	v_add_f32_e32 v116, v83, v116
	v_exp_f32_e32 v132, v122
	v_add_f32_e32 v116, v128, v116
	v_add_f32_e32 v116, v129, v116
	v_exp_f32_e32 v134, v124
	v_add_f32_e32 v116, v130, v116
	v_exp_f32_e32 v135, v125
	v_add_f32_e32 v116, v131, v116
	v_add_f32_e32 v116, v132, v116
	v_add_f32_e32 v116, v133, v116
	v_add_f32_e32 v116, v134, v116
	v_add_f32_e32 v116, v135, v116
	v_add_f32_e32 v116, v214, v116
	v_add_f32_e32 v212, v223, v116
	v_mov_b32_e32 v213, v212
	s_nop 1
	v_permlane32_swap_b32_e32 v212, v213
	v_cvt_pk_bf16_f32 v116, v220, v222
	v_cvt_pk_bf16_f32 v117, v218, v221
	v_cvt_pk_bf16_f32 v118, v217, v219
	v_cvt_pk_bf16_f32 v119, v215, v216
	v_cvt_pk_bf16_f32 v120, v140, v143
	v_cvt_pk_bf16_f32 v121, v138, v141
	v_cvt_pk_bf16_f32 v122, v136, v142
	v_cvt_pk_bf16_f32 v123, v137, v139
	v_cvt_pk_bf16_f32 v124, v0, v1
	v_cvt_pk_bf16_f32 v125, v3, v81
	v_cvt_pk_bf16_f32 v126, v82, v83
	v_cvt_pk_bf16_f32 v127, v128, v129
	v_cvt_pk_bf16_f32 v128, v130, v131
	v_cvt_pk_bf16_f32 v129, v132, v133
	v_cvt_pk_bf16_f32 v130, v134, v135
	v_cvt_pk_bf16_f32 v131, v214, v223
	s_nop 0
	v_permlane32_swap_b32_e32 v116, v118
	v_permlane32_swap_b32_e32 v117, v119
	v_permlane32_swap_b32_e32 v120, v122
	v_permlane32_swap_b32_e32 v121, v123
	v_permlane32_swap_b32_e32 v124, v126
	v_permlane32_swap_b32_e32 v125, v127
	v_permlane32_swap_b32_e32 v128, v130
	v_permlane32_swap_b32_e32 v129, v131
	ds_read_b64_tr_b16 v[132:133], v195 offset:0
	ds_read_b64_tr_b16 v[134:135], v195 offset:0x800
	ds_read_b64_tr_b16 v[136:137], v195 offset:0x1000
	ds_read_b64_tr_b16 v[138:139], v195 offset:0x1800
	ds_read_b64_tr_b16 v[140:141], v195 offset:0x2000
	ds_read_b64_tr_b16 v[142:143], v195 offset:0x2800
	ds_read_b64_tr_b16 v[214:215], v195 offset:0x3000
	ds_read_b64_tr_b16 v[216:217], v195 offset:0x3800
	s_waitcnt lgkmcnt(0)
	s_nop 0
	v_mfma_f32_32x32x16_bf16 v[64:79], v[116:119], v[132:135], v[64:79]
	ds_read_b64_tr_b16 v[132:133], v195 offset:0x200
	ds_read_b64_tr_b16 v[134:135], v195 offset:0xa00
	v_mfma_f32_32x32x16_bf16 v[64:79], v[120:123], v[136:139], v[64:79]
	ds_read_b64_tr_b16 v[136:137], v195 offset:0x1200
	ds_read_b64_tr_b16 v[138:139], v195 offset:0x1a00
	v_mfma_f32_32x32x16_bf16 v[64:79], v[124:127], v[140:143], v[64:79]
	ds_read_b64_tr_b16 v[140:141], v195 offset:0x2200
	ds_read_b64_tr_b16 v[142:143], v195 offset:0x2a00
	ds_read_b64_tr_b16 v[218:219], v195 offset:0x3200
	ds_read_b64_tr_b16 v[220:221], v195 offset:0x3a00
	s_waitcnt lgkmcnt(0)
	v_mfma_f32_32x32x16_bf16 v[64:79], v[128:131], v[214:217], v[64:79]
	v_mfma_f32_32x32x16_bf16 v[48:63], v[116:119], v[132:135], v[48:63]
	ds_read_b64_tr_b16 v[132:133], v195 offset:0x400
	ds_read_b64_tr_b16 v[134:135], v195 offset:0xc00
	v_mfma_f32_32x32x16_bf16 v[48:63], v[120:123], v[136:139], v[48:63]
	ds_read_b64_tr_b16 v[136:137], v195 offset:0x1400
	ds_read_b64_tr_b16 v[138:139], v195 offset:0x1c00
	v_mfma_f32_32x32x16_bf16 v[48:63], v[124:127], v[140:143], v[48:63]
	ds_read_b64_tr_b16 v[140:141], v195 offset:0x2400
	ds_read_b64_tr_b16 v[142:143], v195 offset:0x2c00
	ds_read_b64_tr_b16 v[214:215], v195 offset:0x3400
	ds_read_b64_tr_b16 v[216:217], v195 offset:0x3c00
	s_waitcnt lgkmcnt(0)
	v_mfma_f32_32x32x16_bf16 v[48:63], v[128:131], v[218:221], v[48:63]
	v_mfma_f32_32x32x16_bf16 v[32:47], v[116:119], v[132:135], v[32:47]
	ds_read_b64_tr_b16 v[132:133], v195 offset:0x600
	ds_read_b64_tr_b16 v[134:135], v195 offset:0xe00
	v_mfma_f32_32x32x16_bf16 v[32:47], v[120:123], v[136:139], v[32:47]
	ds_read_b64_tr_b16 v[136:137], v195 offset:0x1600
	ds_read_b64_tr_b16 v[138:139], v195 offset:0x1e00
	v_mfma_f32_32x32x16_bf16 v[32:47], v[124:127], v[140:143], v[32:47]
	ds_read_b64_tr_b16 v[140:141], v195 offset:0x2600
	ds_read_b64_tr_b16 v[142:143], v195 offset:0x2e00
	ds_read_b64_tr_b16 v[218:219], v195 offset:0x3600
	ds_read_b64_tr_b16 v[220:221], v195 offset:0x3e00
	s_waitcnt lgkmcnt(0)
	v_mfma_f32_32x32x16_bf16 v[32:47], v[128:131], v[214:217], v[32:47]
	v_mfma_f32_32x32x16_bf16 v[16:31], v[116:119], v[132:135], v[16:31]
	s_cmp_le_i32 s94, s93
	v_mfma_f32_32x32x16_bf16 v[16:31], v[120:123], v[136:139], v[16:31]
	v_mfma_f32_32x32x16_bf16 v[16:31], v[124:127], v[140:143], v[16:31]
	v_mfma_f32_32x32x16_bf16 v[16:31], v[128:131], v[218:221], v[16:31]
	s_cbranch_scc1 .LBB0_576
	v_cmp_gt_i32_e64 s[62:63], 26, v210
	v_cmp_gt_i32_e64 s[64:65], 27, v210
	v_cmp_gt_i32_e64 s[60:61], 25, v210
	s_and_b64 s[62:63], s[64:65], s[62:63]
	v_cmp_gt_i32_e64 s[58:59], 24, v210
	s_and_b64 s[60:61], s[62:63], s[60:61]
	v_cmp_gt_i32_e64 s[56:57], 19, v210
	s_and_b64 s[58:59], s[60:61], s[58:59]
	v_cmp_gt_i32_e64 s[54:55], 18, v210
	s_and_b64 s[56:57], s[58:59], s[56:57]
	v_cmp_gt_i32_e64 s[52:53], 17, v210
	s_and_b64 s[54:55], s[56:57], s[54:55]
	v_cmp_gt_i32_e64 s[50:51], 16, v210
	s_and_b64 s[52:53], s[54:55], s[52:53]
	v_cmp_gt_i32_e64 s[48:49], 11, v210
	s_and_b64 s[50:51], s[52:53], s[50:51]
	v_cmp_gt_i32_e64 s[46:47], 10, v210
	s_and_b64 s[48:49], s[50:51], s[48:49]
	v_cmp_gt_i32_e64 s[44:45], 9, v210
	s_and_b64 s[46:47], s[48:49], s[46:47]
	v_cmp_gt_i32_e64 s[42:43], 8, v210
	s_and_b64 s[44:45], s[46:47], s[44:45]
	v_cmp_gt_i32_e64 s[40:41], 3, v210
	s_and_b64 s[42:43], s[44:45], s[42:43]
	v_cmp_gt_i32_e64 s[38:39], 2, v210
	s_and_b64 s[40:41], s[42:43], s[40:41]
	v_cmp_gt_i32_e64 s[36:37], 1, v210
	s_and_b64 s[38:39], s[40:41], s[38:39]
	v_cmp_gt_i32_e64 s[34:35], 0, v210
	s_and_b64 s[36:37], s[38:39], s[36:37]
	s_and_b64 s[34:35], s[36:37], s[34:35]
	v_cmp_gt_i32_e64 s[30:31], 58, v210
	v_cndmask_b32_e64 v100, v100, v186, s[34:35]
	v_cmp_gt_i32_e64 s[34:35], 59, v210
	v_cmp_gt_i32_e64 s[28:29], 57, v210
	s_and_b64 s[30:31], s[34:35], s[30:31]
	v_cmp_gt_i32_e64 s[26:27], 56, v210
	s_and_b64 s[28:29], s[30:31], s[28:29]
	v_cmp_gt_i32_e64 s[24:25], 51, v210
	s_and_b64 s[26:27], s[28:29], s[26:27]
	v_cmp_gt_i32_e64 s[22:23], 50, v210
	s_and_b64 s[24:25], s[26:27], s[24:25]
	v_cmp_gt_i32_e64 s[20:21], 49, v210
	s_and_b64 s[22:23], s[24:25], s[22:23]
	v_cmp_gt_i32_e64 s[18:19], 48, v210
	s_and_b64 s[20:21], s[22:23], s[20:21]
	v_cmp_gt_i32_e64 s[16:17], 43, v210
	s_and_b64 s[18:19], s[20:21], s[18:19]
	v_cmp_gt_i32_e64 s[14:15], 42, v210
	s_and_b64 s[16:17], s[18:19], s[16:17]
	v_cmp_gt_i32_e64 s[12:13], 41, v210
	s_and_b64 s[14:15], s[16:17], s[14:15]
	v_cmp_gt_i32_e64 s[10:11], 40, v210
	s_and_b64 s[12:13], s[14:15], s[12:13]
	v_cmp_gt_i32_e64 s[8:9], 35, v210
	s_and_b64 s[10:11], s[12:13], s[10:11]
	v_cmp_gt_i32_e64 s[6:7], 34, v210
	s_and_b64 s[8:9], s[10:11], s[8:9]
	v_cmp_gt_i32_e64 s[4:5], 33, v210
	s_and_b64 s[6:7], s[8:9], s[6:7]
	v_cmp_gt_i32_e32 vcc, 32, v210
	s_and_b64 s[4:5], s[6:7], s[4:5]
	s_and_b64 vcc, s[4:5], vcc
	v_cndmask_b32_e64 v115, v115, v186, s[64:65]
	v_cndmask_b32_e64 v114, v114, v186, s[62:63]
	v_cndmask_b32_e64 v113, v113, v186, s[60:61]
	v_cndmask_b32_e64 v112, v112, v186, s[58:59]
	v_cndmask_b32_e64 v111, v111, v186, s[56:57]
	v_cndmask_b32_e64 v110, v110, v186, s[54:55]
	v_cndmask_b32_e64 v109, v109, v186, s[52:53]
	v_cndmask_b32_e64 v108, v108, v186, s[50:51]
	v_cndmask_b32_e64 v107, v107, v186, s[48:49]
	v_cndmask_b32_e64 v106, v106, v186, s[46:47]
	v_cndmask_b32_e64 v105, v105, v186, s[44:45]
	v_cndmask_b32_e64 v104, v104, v186, s[42:43]
	v_cndmask_b32_e64 v103, v103, v186, s[40:41]
	v_cndmask_b32_e64 v102, v102, v186, s[38:39]
	v_cndmask_b32_e64 v101, v101, v186, s[36:37]
	v_cndmask_b32_e64 v99, v99, v186, s[34:35]
	v_cndmask_b32_e64 v98, v98, v186, s[30:31]
	v_cndmask_b32_e64 v97, v97, v186, s[28:29]
	v_cndmask_b32_e64 v96, v96, v186, s[26:27]
	v_cndmask_b32_e64 v95, v95, v186, s[24:25]
	v_cndmask_b32_e64 v94, v94, v186, s[22:23]
	v_cndmask_b32_e64 v93, v93, v186, s[20:21]
	v_cndmask_b32_e64 v92, v92, v186, s[18:19]
	v_cndmask_b32_e64 v91, v91, v186, s[16:17]
	v_cndmask_b32_e64 v90, v90, v186, s[14:15]
	v_cndmask_b32_e64 v89, v89, v186, s[12:13]
	v_cndmask_b32_e64 v88, v88, v186, s[10:11]
	v_cndmask_b32_e64 v87, v87, v186, s[8:9]
	v_cndmask_b32_e64 v86, v86, v186, s[6:7]
	v_cndmask_b32_e64 v85, v85, v186, s[4:5]
	v_cndmask_b32_e32 v84, v84, v186, vcc

.LBB0_582:
	v_cndmask_b32_e64 v208, v0, v208, s[4:5]
	v_mul_f32_e32 v215, 0xbe0293ee, v208
	v_fmamk_f32 v0, v100, 0x3e0293ee, v215
	v_fmamk_f32 v1, v101, 0x3e0293ee, v215
	v_fmamk_f32 v3, v102, 0x3e0293ee, v215
	v_fmamk_f32 v83, v103, 0x3e0293ee, v215
	v_fmamk_f32 v100, v104, 0x3e0293ee, v215
	v_fmamk_f32 v101, v105, 0x3e0293ee, v215
	v_fmamk_f32 v102, v106, 0x3e0293ee, v215
	v_fmamk_f32 v103, v107, 0x3e0293ee, v215
	v_fmamk_f32 v104, v108, 0x3e0293ee, v215
	v_fmamk_f32 v105, v109, 0x3e0293ee, v215
	v_fmamk_f32 v106, v110, 0x3e0293ee, v215
	v_fmamk_f32 v107, v111, 0x3e0293ee, v215
	v_fmamk_f32 v108, v112, 0x3e0293ee, v215
	v_fmamk_f32 v109, v113, 0x3e0293ee, v215
	v_fmamk_f32 v110, v114, 0x3e0293ee, v215
	v_fmamk_f32 v111, v115, 0x3e0293ee, v215
	v_fmamk_f32 v216, v84, 0x3e0293ee, v215
	v_fmamk_f32 v217, v85, 0x3e0293ee, v215
	v_fmamk_f32 v218, v86, 0x3e0293ee, v215
	v_fmamk_f32 v219, v87, 0x3e0293ee, v215
	v_fmamk_f32 v220, v88, 0x3e0293ee, v215
	v_fmamk_f32 v221, v89, 0x3e0293ee, v215
	v_fmamk_f32 v222, v90, 0x3e0293ee, v215
	v_fmamk_f32 v223, v91, 0x3e0293ee, v215
	v_fmamk_f32 v224, v92, 0x3e0293ee, v215
	v_fmamk_f32 v225, v93, 0x3e0293ee, v215
	v_fmamk_f32 v226, v94, 0x3e0293ee, v215
	v_fmamk_f32 v227, v95, 0x3e0293ee, v215
	v_exp_f32_e32 v80, v0
	v_exp_f32_e32 v81, v1
	v_exp_f32_e32 v82, v3
	v_exp_f32_e32 v83, v83
	v_exp_f32_e32 v84, v100
	v_exp_f32_e32 v85, v101
	v_exp_f32_e32 v86, v102
	v_exp_f32_e32 v87, v103
	v_exp_f32_e32 v88, v104
	v_exp_f32_e32 v89, v105
	v_exp_f32_e32 v90, v106
	v_exp_f32_e32 v91, v107
	v_exp_f32_e32 v92, v108
	v_exp_f32_e32 v93, v109
	v_exp_f32_e32 v94, v110
	v_exp_f32_e32 v95, v111
	v_fmamk_f32 v110, v97, 0x3e0293ee, v215
	v_fmamk_f32 v111, v98, 0x3e0293ee, v215
	v_fmamk_f32 v228, v96, 0x3e0293ee, v215
	v_fmac_f32_e32 v215, 0x3e0293ee, v99
	ds_read2_b32 v[108:109], v211 offset1:32
	ds_read_b128 v[96:99], v202 offset:32768
	ds_read_b128 v[100:103], v202 offset:40960
	s_waitcnt lgkmcnt(1)
	v_mfma_f32_32x32x16_bf16 v[128:143], v[96:99], v[156:159], 0
	v_and_b32_e32 v0, 0xffff0000, v108
	v_sub_f32_e32 v0, v108, v0
	v_and_b32_e32 v3, 0xffff0000, v109
	v_and_b32_e32 v1, 0xffff0000, v0
	v_sub_f32_e32 v3, v109, v3
	v_sub_f32_e32 v0, v0, v1
	v_lshrrev_b32_e32 v0, 16, v0
	s_waitcnt lgkmcnt(0)
	v_mfma_f32_32x32x16_bf16 v[112:127], v[100:103], v[156:159], 0
	ds_read_b128 v[96:99], v203 offset:32768
	ds_read_b128 v[100:103], v203 offset:40960
	s_waitcnt lgkmcnt(1)
	v_mfma_f32_32x32x16_bf16 v[128:143], v[96:99], v[152:155], v[128:143]
	s_waitcnt lgkmcnt(0)
	v_mfma_f32_32x32x16_bf16 v[112:127], v[100:103], v[152:155], v[112:127]
	ds_read_b128 v[96:99], v204 offset:32768
	ds_read_b128 v[100:103], v204 offset:40960
	s_waitcnt lgkmcnt(1)
	v_mfma_f32_32x32x16_bf16 v[128:143], v[96:99], v[148:151], v[128:143]
	s_waitcnt lgkmcnt(0)
	v_mfma_f32_32x32x16_bf16 v[112:127], v[100:103], v[148:151], v[112:127]
	ds_read_b128 v[96:99], v205 offset:32768
	ds_read_b128 v[100:103], v205 offset:40960
	s_waitcnt lgkmcnt(1)
	v_mfma_f32_32x32x16_bf16 v[128:143], v[96:99], v[144:147], v[128:143]
	s_waitcnt lgkmcnt(0)
	v_mfma_f32_32x32x16_bf16 v[112:127], v[100:103], v[144:147], v[112:127]
	ds_read_b128 v[96:99], v252 offset:32768
	ds_read_b128 v[100:103], v252 offset:40960
	ds_read_b128 v[104:107], v175
	s_waitcnt lgkmcnt(0)
	v_mfma_f32_32x32x16_bf16 v[128:143], v[96:99], v[104:107], v[128:143]
	v_mfma_f32_32x32x16_bf16 v[112:127], v[100:103], v[104:107], v[112:127]
	ds_read_b128 v[96:99], v253 offset:32768
	ds_read_b128 v[100:103], v253 offset:40960
	ds_read_b128 v[104:107], v175 offset:1024
	s_waitcnt lgkmcnt(0)
	v_mfma_f32_32x32x16_bf16 v[128:143], v[96:99], v[104:107], v[128:143]
	v_mfma_f32_32x32x16_bf16 v[112:127], v[100:103], v[104:107], v[112:127]
	ds_read_b128 v[96:99], v254 offset:32768
	ds_read_b128 v[100:103], v254 offset:40960
	ds_read_b128 v[104:107], v175 offset:2048
	s_waitcnt lgkmcnt(0)
	v_mfma_f32_32x32x16_bf16 v[128:143], v[96:99], v[104:107], v[128:143]
	v_mfma_f32_32x32x16_bf16 v[112:127], v[100:103], v[104:107], v[112:127]
	ds_read_b128 v[96:99], v176 offset:32768
	ds_read_b128 v[100:103], v176 offset:40960
	ds_read_b128 v[104:107], v175 offset:3072
	s_waitcnt lgkmcnt(0)
	v_mfma_f32_32x32x16_bf16 v[128:143], v[96:99], v[104:107], v[128:143]
	v_and_b32_e32 v96, 0xffff0000, v3
	v_sub_f32_e32 v3, v3, v96
	v_or_b32_sdwa v97, v1, v108 dst_sel:DWORD dst_unused:UNUSED_PAD src0_sel:DWORD src1_sel:WORD_1
	v_cndmask_b32_e64 v1, 0, v0, s[2:3]
	v_or_b32_sdwa v0, v96, v109 dst_sel:DWORD dst_unused:UNUSED_PAD src0_sel:DWORD src1_sel:WORD_1
	v_lshrrev_b32_e32 v3, 16, v3
	v_cndmask_b32_e64 v96, 0, v0, s[2:3]
	v_cndmask_b32_e64 v0, 0, v97, s[2:3]
	v_cndmask_b32_e64 v97, 0, v3, s[2:3]
	v_mov_b32_e32 v3, v2
	v_mfma_f32_32x32x16_bf16 v[112:127], v[100:103], v[104:107], v[112:127]
	v_mov_b64_e32 v[102:103], s[70:71]
	v_mov_b64_e32 v[100:101], s[68:69]
	v_mov_b32_e32 v98, v2
	v_mov_b32_e32 v99, v2
	v_exp_f32_e32 v104, v224
	v_exp_f32_e32 v105, v225
	v_exp_f32_e32 v106, v226
	v_mfma_f32_32x32x16_bf16 v[128:143], v[0:3], v[100:103], v[128:143]
	v_add_f32_e32 v0, 0, v80
	v_add_f32_e32 v0, v81, v0
	v_add_f32_e32 v0, v82, v0
	v_add_f32_e32 v0, v83, v0
	v_add_f32_e32 v0, v84, v0
	v_add_f32_e32 v0, v85, v0
	v_add_f32_e32 v0, v86, v0
	v_add_f32_e32 v0, v87, v0
	v_add_f32_e32 v0, v88, v0
	v_add_f32_e32 v0, v89, v0
	v_add_f32_e32 v0, v90, v0
	v_add_f32_e32 v0, v91, v0
	v_mfma_f32_32x32x16_bf16 v[112:127], v[96:99], v[100:103], v[112:127]
	v_exp_f32_e32 v96, v216
	v_add_f32_e32 v0, v92, v0
	v_exp_f32_e32 v97, v217
	v_add_f32_e32 v0, v93, v0
	v_exp_f32_e32 v98, v218
	v_add_f32_e32 v0, v94, v0
	v_exp_f32_e32 v99, v219
	v_add_f32_e32 v0, v95, v0
	v_exp_f32_e32 v100, v220
	v_add_f32_e32 v0, v96, v0
	v_exp_f32_e32 v101, v221
	v_add_f32_e32 v0, v97, v0
	v_exp_f32_e32 v102, v222
	v_add_f32_e32 v0, v98, v0
	v_exp_f32_e32 v103, v223
	v_add_f32_e32 v0, v99, v0
	v_add_f32_e32 v0, v100, v0
	v_add_f32_e32 v0, v101, v0
	v_add_f32_e32 v0, v102, v0
	v_exp_f32_e32 v107, v227
	v_add_f32_e32 v0, v103, v0
	v_exp_f32_e32 v108, v228
	v_add_f32_e32 v0, v104, v0
	v_exp_f32_e32 v109, v110
	v_add_f32_e32 v0, v105, v0
	v_exp_f32_e32 v110, v111
	v_add_f32_e32 v0, v106, v0
	v_exp_f32_e32 v111, v215
	v_add_f32_e32 v0, v107, v0
	v_add_f32_e32 v0, v108, v0
	v_add_f32_e32 v0, v109, v0
	v_add_f32_e32 v0, v110, v0
	v_add_f32_e32 v1, v111, v0
	v_mov_b32_e32 v3, v1
	s_nop 1
	v_permlane32_swap_b32_e32 v1, v3
	v_cvt_pk_bf16_f32 v216, v80, v81
	v_cvt_pk_bf16_f32 v217, v82, v83
	v_cvt_pk_bf16_f32 v218, v84, v85
	v_cvt_pk_bf16_f32 v219, v86, v87
	v_cvt_pk_bf16_f32 v220, v88, v89
	v_cvt_pk_bf16_f32 v221, v90, v91
	v_cvt_pk_bf16_f32 v222, v92, v93
	v_cvt_pk_bf16_f32 v223, v94, v95
	v_cvt_pk_bf16_f32 v224, v96, v97
	v_cvt_pk_bf16_f32 v225, v98, v99
	v_cvt_pk_bf16_f32 v226, v100, v101
	v_cvt_pk_bf16_f32 v227, v102, v103
	v_cvt_pk_bf16_f32 v228, v104, v105
	v_cvt_pk_bf16_f32 v229, v106, v107
	v_cvt_pk_bf16_f32 v230, v108, v109
	v_cvt_pk_bf16_f32 v231, v110, v111
	s_nop 0
	v_permlane32_swap_b32_e32 v216, v218
	v_permlane32_swap_b32_e32 v217, v219
	v_permlane32_swap_b32_e32 v220, v222
	v_permlane32_swap_b32_e32 v221, v223
	v_permlane32_swap_b32_e32 v224, v226
	v_permlane32_swap_b32_e32 v225, v227
	v_permlane32_swap_b32_e32 v228, v230
	v_permlane32_swap_b32_e32 v229, v231
	ds_read_b64_tr_b16 v[232:233], v195 offset:0x4000
	ds_read_b64_tr_b16 v[234:235], v195 offset:0x4800
	ds_read_b64_tr_b16 v[236:237], v195 offset:0x5000
	ds_read_b64_tr_b16 v[238:239], v195 offset:0x5800
	ds_read_b64_tr_b16 v[240:241], v195 offset:0x6000
	ds_read_b64_tr_b16 v[242:243], v195 offset:0x6800
	ds_read_b64_tr_b16 v[244:245], v195 offset:0x7000
	ds_read_b64_tr_b16 v[246:247], v195 offset:0x7800
	s_waitcnt lgkmcnt(0)
	s_nop 0
	v_mfma_f32_32x32x16_bf16 v[64:79], v[216:219], v[232:235], v[64:79]
	ds_read_b64_tr_b16 v[232:233], v195 offset:0x4200
	ds_read_b64_tr_b16 v[234:235], v195 offset:0x4a00
	v_mfma_f32_32x32x16_bf16 v[64:79], v[220:223], v[236:239], v[64:79]
	ds_read_b64_tr_b16 v[236:237], v195 offset:0x5200
	ds_read_b64_tr_b16 v[238:239], v195 offset:0x5a00
	v_mfma_f32_32x32x16_bf16 v[64:79], v[224:227], v[240:243], v[64:79]
	ds_read_b64_tr_b16 v[240:241], v195 offset:0x6200
	ds_read_b64_tr_b16 v[242:243], v195 offset:0x6a00
	ds_read_b64_tr_b16 v[248:249], v195 offset:0x7200
	ds_read_b64_tr_b16 v[250:251], v195 offset:0x7a00
	s_waitcnt lgkmcnt(0)
	v_mfma_f32_32x32x16_bf16 v[64:79], v[228:231], v[244:247], v[64:79]
	v_mfma_f32_32x32x16_bf16 v[48:63], v[216:219], v[232:235], v[48:63]
	ds_read_b64_tr_b16 v[232:233], v195 offset:0x4400
	ds_read_b64_tr_b16 v[234:235], v195 offset:0x4c00
	v_mfma_f32_32x32x16_bf16 v[48:63], v[220:223], v[236:239], v[48:63]
	ds_read_b64_tr_b16 v[236:237], v195 offset:0x5400
	ds_read_b64_tr_b16 v[238:239], v195 offset:0x5c00
	v_mfma_f32_32x32x16_bf16 v[48:63], v[224:227], v[240:243], v[48:63]
	ds_read_b64_tr_b16 v[240:241], v195 offset:0x6400
	ds_read_b64_tr_b16 v[242:243], v195 offset:0x6c00
	ds_read_b64_tr_b16 v[244:245], v195 offset:0x7400
	ds_read_b64_tr_b16 v[246:247], v195 offset:0x7c00
	s_waitcnt lgkmcnt(0)
	v_mfma_f32_32x32x16_bf16 v[48:63], v[228:231], v[248:251], v[48:63]
	v_mfma_f32_32x32x16_bf16 v[32:47], v[216:219], v[232:235], v[32:47]
	ds_read_b64_tr_b16 v[232:233], v195 offset:0x4600
	ds_read_b64_tr_b16 v[234:235], v195 offset:0x4e00
	v_mfma_f32_32x32x16_bf16 v[32:47], v[220:223], v[236:239], v[32:47]
	ds_read_b64_tr_b16 v[236:237], v195 offset:0x5600
	ds_read_b64_tr_b16 v[238:239], v195 offset:0x5e00
	v_mfma_f32_32x32x16_bf16 v[32:47], v[224:227], v[240:243], v[32:47]
	ds_read_b64_tr_b16 v[240:241], v195 offset:0x6600
	ds_read_b64_tr_b16 v[242:243], v195 offset:0x6e00
	ds_read_b64_tr_b16 v[248:249], v195 offset:0x7600
	ds_read_b64_tr_b16 v[250:251], v195 offset:0x7e00
	s_waitcnt lgkmcnt(0)
	v_mfma_f32_32x32x16_bf16 v[32:47], v[228:231], v[244:247], v[32:47]
	v_mfma_f32_32x32x16_bf16 v[16:31], v[216:219], v[232:235], v[16:31]
	s_sub_i32 s4, s94, 64
	s_cmp_le_i32 s4, s93
	v_mfma_f32_32x32x16_bf16 v[16:31], v[220:223], v[236:239], v[16:31]
	v_mfma_f32_32x32x16_bf16 v[16:31], v[224:227], v[240:243], v[16:31]
	v_mfma_f32_32x32x16_bf16 v[16:31], v[228:231], v[248:251], v[16:31]
	s_cbranch_scc1 .LBB0_584
	v_add_u32_e32 v0, 64, v210
	v_cmp_gt_i32_e64 s[62:63], 26, v0
	v_cmp_gt_i32_e64 s[64:65], 27, v0
	v_cmp_gt_i32_e64 s[60:61], 25, v0
	s_and_b64 s[62:63], s[64:65], s[62:63]
	v_cmp_gt_i32_e64 s[58:59], 24, v0
	s_and_b64 s[60:61], s[62:63], s[60:61]
	v_cmp_gt_i32_e64 s[56:57], 19, v0
	s_and_b64 s[58:59], s[60:61], s[58:59]
	v_cmp_gt_i32_e64 s[54:55], 18, v0
	s_and_b64 s[56:57], s[58:59], s[56:57]
	v_cmp_gt_i32_e64 s[52:53], 17, v0
	s_and_b64 s[54:55], s[56:57], s[54:55]
	v_cmp_gt_i32_e64 s[50:51], 16, v0
	s_and_b64 s[52:53], s[54:55], s[52:53]
	v_cmp_gt_i32_e64 s[48:49], 11, v0
	s_and_b64 s[50:51], s[52:53], s[50:51]
	v_cmp_gt_i32_e64 s[46:47], 10, v0
	s_and_b64 s[48:49], s[50:51], s[48:49]
	v_cmp_gt_i32_e64 s[44:45], 9, v0
	s_and_b64 s[46:47], s[48:49], s[46:47]
	v_cmp_gt_i32_e64 s[42:43], 8, v0
	s_and_b64 s[44:45], s[46:47], s[44:45]
	v_cmp_gt_i32_e64 s[40:41], 3, v0
	s_and_b64 s[42:43], s[44:45], s[42:43]
	v_cmp_gt_i32_e64 s[38:39], 2, v0
	s_and_b64 s[40:41], s[42:43], s[40:41]
	v_cmp_gt_i32_e64 s[36:37], 1, v0
	s_and_b64 s[38:39], s[40:41], s[38:39]
	v_cmp_gt_i32_e64 s[34:35], 0, v0
	s_and_b64 s[36:37], s[38:39], s[36:37]
	s_and_b64 s[34:35], s[36:37], s[34:35]
	v_cmp_gt_i32_e64 s[30:31], 58, v0
	v_cndmask_b32_e64 v128, v128, v186, s[34:35]
	v_cmp_gt_i32_e64 s[34:35], 59, v0
	v_cmp_gt_i32_e64 s[28:29], 57, v0
	s_and_b64 s[30:31], s[34:35], s[30:31]
	v_cmp_gt_i32_e64 s[26:27], 56, v0
	s_and_b64 s[28:29], s[30:31], s[28:29]
	v_cmp_gt_i32_e64 s[24:25], 51, v0
	s_and_b64 s[26:27], s[28:29], s[26:27]
	v_cmp_gt_i32_e64 s[22:23], 50, v0
	s_and_b64 s[24:25], s[26:27], s[24:25]
	v_cmp_gt_i32_e64 s[20:21], 49, v0
	s_and_b64 s[22:23], s[24:25], s[22:23]
	v_cmp_gt_i32_e64 s[18:19], 48, v0
	s_and_b64 s[20:21], s[22:23], s[20:21]
	v_cmp_gt_i32_e64 s[16:17], 43, v0
	s_and_b64 s[18:19], s[20:21], s[18:19]
	v_cmp_gt_i32_e64 s[14:15], 42, v0
	s_and_b64 s[16:17], s[18:19], s[16:17]
	v_cmp_gt_i32_e64 s[12:13], 41, v0
	s_and_b64 s[14:15], s[16:17], s[14:15]
	v_cmp_gt_i32_e64 s[10:11], 40, v0
	s_and_b64 s[12:13], s[14:15], s[12:13]
	v_cmp_gt_i32_e64 s[8:9], 35, v0
	s_and_b64 s[10:11], s[12:13], s[10:11]
	v_cmp_gt_i32_e64 s[6:7], 34, v0
	s_and_b64 s[8:9], s[10:11], s[8:9]
	v_cmp_gt_i32_e64 s[4:5], 33, v0
	s_and_b64 s[6:7], s[8:9], s[6:7]
	v_cmp_gt_i32_e32 vcc, 32, v0
	s_and_b64 s[4:5], s[6:7], s[4:5]
	s_and_b64 vcc, s[4:5], vcc
	v_cndmask_b32_e64 v143, v143, v186, s[64:65]
	v_cndmask_b32_e64 v142, v142, v186, s[62:63]
	v_cndmask_b32_e64 v141, v141, v186, s[60:61]
	v_cndmask_b32_e64 v140, v140, v186, s[58:59]
	v_cndmask_b32_e64 v139, v139, v186, s[56:57]
	v_cndmask_b32_e64 v138, v138, v186, s[54:55]
	v_cndmask_b32_e64 v137, v137, v186, s[52:53]
	v_cndmask_b32_e64 v136, v136, v186, s[50:51]
	v_cndmask_b32_e64 v135, v135, v186, s[48:49]
	v_cndmask_b32_e64 v134, v134, v186, s[46:47]
	v_cndmask_b32_e64 v133, v133, v186, s[44:45]
	v_cndmask_b32_e64 v132, v132, v186, s[42:43]
	v_cndmask_b32_e64 v131, v131, v186, s[40:41]
	v_cndmask_b32_e64 v130, v130, v186, s[38:39]
	v_cndmask_b32_e64 v129, v129, v186, s[36:37]
	v_cndmask_b32_e64 v127, v127, v186, s[34:35]
	v_cndmask_b32_e64 v126, v126, v186, s[30:31]
	v_cndmask_b32_e64 v125, v125, v186, s[28:29]
	v_cndmask_b32_e64 v124, v124, v186, s[26:27]
	v_cndmask_b32_e64 v123, v123, v186, s[24:25]
	v_cndmask_b32_e64 v122, v122, v186, s[22:23]
	v_cndmask_b32_e64 v121, v121, v186, s[20:21]
	v_cndmask_b32_e64 v120, v120, v186, s[18:19]
	v_cndmask_b32_e64 v119, v119, v186, s[16:17]
	v_cndmask_b32_e64 v118, v118, v186, s[14:15]
	v_cndmask_b32_e64 v117, v117, v186, s[12:13]
	v_cndmask_b32_e64 v116, v116, v186, s[10:11]
	v_cndmask_b32_e64 v115, v115, v186, s[8:9]
	v_cndmask_b32_e64 v114, v114, v186, s[6:7]
	v_cndmask_b32_e64 v113, v113, v186, s[4:5]
	v_cndmask_b32_e32 v112, v112, v186, vcc

.LBB0_591:
	s_waitcnt vmcnt(3)
	ds_write_b128 v200, v[164:167] offset:16384
	s_waitcnt vmcnt(2)
	ds_write_b128 v201, v[168:171] offset:16384
	ds_read_b128 v[4:7], v202 offset:49152
	ds_read_b128 v[8:11], v252 offset:49152
	v_lshl_add_u32 v0, s74, 8, v199
	s_mov_b64 vcc, s[2:3]
	s_waitcnt lgkmcnt(1)
	v_mfma_f32_32x32x16_bf16 v[80:95], v[4:7], v[156:159], 0
	ds_read_b128 v[4:7], v202 offset:57344
	ds_read_b128 v[12:15], v252 offset:57344
	s_waitcnt lgkmcnt(1)
	v_mfma_f32_32x32x16_bf16 v[96:111], v[4:7], v[156:159], 0
	ds_read_b128 v[4:7], v203 offset:49152
	s_waitcnt vmcnt(1)
	ds_read_b128 v[112:115], v253 offset:49152
	s_waitcnt lgkmcnt(1)
	v_mfma_f32_32x32x16_bf16 v[80:95], v[4:7], v[152:155], v[80:95]
	ds_read_b128 v[4:7], v203 offset:57344
	s_waitcnt vmcnt(0)
	ds_read_b128 v[116:119], v253 offset:57344
	s_waitcnt lgkmcnt(1)
	v_mfma_f32_32x32x16_bf16 v[96:111], v[4:7], v[152:155], v[96:111]
	ds_read_b128 v[4:7], v204 offset:49152
	ds_read_b128 v[152:155], v254 offset:49152
	s_waitcnt lgkmcnt(1)
	v_mfma_f32_32x32x16_bf16 v[80:95], v[4:7], v[148:151], v[80:95]
	ds_read_b128 v[4:7], v204 offset:57344
	ds_read_b128 v[156:159], v254 offset:57344
	s_waitcnt lgkmcnt(1)
	v_mfma_f32_32x32x16_bf16 v[96:111], v[4:7], v[148:151], v[96:111]
	ds_read_b128 v[4:7], v205 offset:49152
	ds_read_b128 v[148:151], v176 offset:49152
	s_waitcnt lgkmcnt(1)
	v_mfma_f32_32x32x16_bf16 v[80:95], v[4:7], v[144:147], v[80:95]
	ds_read_b128 v[4:7], v205 offset:57344
	ds_read_b128 v[164:167], v176 offset:57344
	s_waitcnt lgkmcnt(1)
	v_mfma_f32_32x32x16_bf16 v[96:111], v[4:7], v[144:147], v[96:111]
	ds_read_b128 v[4:7], v175
	ds_read_b128 v[144:147], v175 offset:1024
	s_waitcnt lgkmcnt(1)
	v_mfma_f32_32x32x16_bf16 v[80:95], v[8:11], v[4:7], v[80:95]
	v_mfma_f32_32x32x16_bf16 v[96:111], v[12:15], v[4:7], v[96:111]
	ds_read_b128 v[4:7], v175 offset:2048
	ds_read_b128 v[8:11], v175 offset:3072
	s_waitcnt lgkmcnt(2)
	v_mfma_f32_32x32x16_bf16 v[80:95], v[112:115], v[144:147], v[80:95]
	v_mfma_f32_32x32x16_bf16 v[96:111], v[116:119], v[144:147], v[96:111]
	s_waitcnt lgkmcnt(1)
	v_mfma_f32_32x32x16_bf16 v[80:95], v[152:155], v[4:7], v[80:95]
	v_mfma_f32_32x32x16_bf16 v[96:111], v[156:159], v[4:7], v[96:111]
	ds_read2_b32 v[4:5], v0 offset1:32
	s_waitcnt lgkmcnt(0)
	v_and_b32_e32 v0, 0xffff0000, v4
	v_and_b32_e32 v3, 0xffff0000, v5
	v_mfma_f32_32x32x16_bf16 v[80:95], v[148:151], v[8:11], v[80:95]
	v_sub_f32_e32 v0, v4, v0
	v_sub_f32_e32 v6, v5, v3
	v_and_b32_e32 v1, 0xffff0000, v0
	v_and_b32_e32 v7, 0xffff0000, v6
	v_or_b32_sdwa v3, v1, v4 dst_sel:DWORD dst_unused:UNUSED_PAD src0_sel:DWORD src1_sel:WORD_1
	v_sub_f32_e32 v0, v0, v1
	v_sub_f32_e32 v6, v6, v7
	v_mfma_f32_32x32x16_bf16 v[96:111], v[164:167], v[8:11], v[96:111]
	v_or_b32_sdwa v4, v7, v5 dst_sel:DWORD dst_unused:UNUSED_PAD src0_sel:DWORD src1_sel:WORD_1
	v_cndmask_b32_sdwa v1, v2, v0, vcc dst_sel:DWORD dst_unused:UNUSED_PAD src0_sel:DWORD src1_sel:WORD_1
	v_cndmask_b32_e64 v0, 0, v3, s[2:3]
	v_mov_b32_e32 v3, v2
	v_cndmask_b32_e64 v4, 0, v4, s[2:3]
	v_cndmask_b32_sdwa v5, v2, v6, vcc dst_sel:DWORD dst_unused:UNUSED_PAD src0_sel:DWORD src1_sel:WORD_1
	v_mov_b32_e32 v6, v2
	v_mov_b32_e32 v7, v2
	v_mov_b64_e32 v[8:9], s[68:69]
	v_mov_b64_e32 v[10:11], s[70:71]
	s_nop 1
	v_mfma_f32_32x32x16_bf16 v[80:95], v[0:3], v[8:11], v[80:95]
	v_mfma_f32_32x32x16_bf16 v[96:111], v[4:7], v[8:11], v[96:111]

.LBB0_743:
	v_writelane_b32 v255, s92, 55
	v_mbcnt_lo_u32_b32 v176, -1, 0
	v_mbcnt_hi_u32_b32 v176, -1, v176
	v_and_b32_e32 v0, 63, v176
	v_lshlrev_b32_e32 v0, 2, v0
	v_writelane_b32 v255, s93, 56
	s_waitcnt lgkmcnt(0)
	v_mov_b32_e32 v1, 0
	v_readlane_b32 s0, v255, 6
	v_readlane_b32 s2, v255, 8
	v_readlane_b32 s8, v255, 10
	v_readlane_b32 s6, v255, 12
	v_readlane_b32 s1, v255, 7
	v_readlane_b32 s3, v255, 9
	v_readlane_b32 s9, v255, 11
	v_readlane_b32 s7, v255, 13
	s_nop 1
	global_load_dword v4, v0, s[0:1]
	global_load_dword v22, v0, s[2:3]
	global_load_dword v23, v0, s[2:3] offset:256
	global_load_dword v24, v0, s[8:9]
	global_load_dword v25, v0, s[6:7]
	global_load_dword v26, v0, s[6:7] offset:256
	global_load_dword v27, v0, s[8:9] offset:256
	global_load_dword v28, v0, s[0:1] offset:256
	s_mul_i32 s0, s12, s86
	s_add_i32 s0, s0, s68
	s_add_i32 s1, s0, 0xfffffe00
	s_and_b32 s3, s0, 7
	s_ashr_i32 s5, s1, 6
	s_bfe_u32 s10, s0, 0x30003
	v_readlane_b32 s0, v255, 2
	v_readlane_b32 s1, v255, 3
	s_add_u32 s18, s0, 0x28100000
	s_addc_u32 s19, s1, 0
	s_mul_i32 s0, s5, 0x60
	s_lshl_b32 s6, s10, 1
	s_or_b32 s1, s0, s6
	s_add_i32 s8, s1, 48
	s_ashr_i32 s9, s8, 31
	s_lshl_b64 s[8:9], s[8:9], 20
	s_add_u32 s2, s18, s8
	s_addc_u32 s7, s19, s9
	s_lshl_b32 s8, s3, 16
	s_add_u32 s12, s2, s8
	s_addc_u32 s13, s7, 0
	s_add_i32 s8, s1, 64
	s_ashr_i32 s9, s8, 31
	s_lshl_b64 s[8:9], s[8:9], 20
	s_add_u32 s8, s18, s8
	v_readlane_b32 s1, v255, 16
	s_addc_u32 s9, s19, s9
	s_bfe_u32 s1, s1, 0x30006
	s_waitcnt vmcnt(8)
	v_mbcnt_lo_u32_b32 v5, -1, 0
	v_mbcnt_hi_u32_b32 v5, -1, v5
	s_lshl_b32 s2, s1, 12
	v_lshlrev_b32_e32 v0, 7, v5
	v_and_b32_e32 v0, 0xf80, v0
	v_or_b32_e32 v0, s2, v0
	v_lshlrev_b32_e32 v0, 1, v0
	v_lshl_add_u64 v[2:3], s[12:13], 0, v[0:1]
	v_lshrrev_b32_e32 v0, 1, v5
	v_and_b32_e32 v0, 16, v0
	v_lshl_add_u64 v[2:3], v[2:3], 0, v[0:1]
	global_load_dwordx4 v[6:9], v[2:3], off offset:128
	global_load_dwordx4 v[10:13], v[2:3], off offset:160
	global_load_dwordx4 v[14:17], v[2:3], off offset:192
	global_load_dwordx4 v[18:21], v[2:3], off offset:224
	global_load_dwordx4 v[162:165], v[2:3], off
	global_load_dwordx4 v[166:169], v[2:3], off offset:32
	global_load_dwordx4 v[170:173], v[2:3], off offset:64
	global_load_dwordx4 v[174:177], v[2:3], off offset:96
	v_mbcnt_lo_u32_b32 v0, -1, 0
	v_mbcnt_hi_u32_b32 v0, -1, v0
	v_and_b32_e32 v2, 64, v0
	v_xor_b32_e32 v3, 1, v0
	v_add_u32_e32 v34, 64, v2
	v_cmp_lt_i32_e32 vcc, v3, v34
	v_xor_b32_e32 v29, 2, v0
	v_xor_b32_e32 v30, 4, v0
	v_cndmask_b32_e32 v3, v0, v3, vcc
	v_lshlrev_b32_e32 v3, 2, v3
	v_cmp_lt_i32_e32 vcc, v29, v34
	v_xor_b32_e32 v31, 8, v0
	v_xor_b32_e32 v32, 16, v0
	v_cndmask_b32_e32 v29, v0, v29, vcc
	v_cmp_lt_i32_e32 vcc, v30, v34
	v_xor_b32_e32 v33, 32, v0
	s_add_i32 s7, s2, 0
	v_cndmask_b32_e32 v30, v0, v30, vcc
	v_cmp_lt_i32_e32 vcc, v31, v34
	v_and_b32_e32 v2, 63, v5
	s_add_i32 s20, s7, 0x19000
	v_cndmask_b32_e32 v31, v0, v31, vcc
	v_cmp_lt_i32_e32 vcc, v32, v34
	s_cmp_lt_u32 s1, 4
	s_cselect_b64 s[92:93], -1, 0
	s_cmp_gt_u32 s1, 3
	s_cselect_b64 s[94:95], -1, 0
	s_waitcnt vmcnt(9)
	v_mul_f32_e32 v26, v27, v26
	s_waitcnt vmcnt(8)
	v_mul_f32_e32 v23, v28, v23
	v_fmac_f32_e32 v23, v4, v22
	v_fmac_f32_e32 v26, v24, v25
	ds_bpermute_b32 v4, v3, v23
	ds_bpermute_b32 v3, v3, v26
	v_lshlrev_b32_e32 v24, 2, v29
	v_lshlrev_b32_e32 v25, 2, v30
	v_cndmask_b32_e32 v22, v0, v32, vcc
	s_waitcnt lgkmcnt(1)
	v_add_f32_e32 v4, v23, v4
	s_waitcnt lgkmcnt(0)
	v_add_f32_e32 v3, v26, v3
	ds_bpermute_b32 v23, v24, v4
	ds_bpermute_b32 v24, v24, v3
	v_lshlrev_b32_e32 v22, 2, v22
	v_cmp_lt_i32_e32 vcc, v33, v34
	s_waitcnt lgkmcnt(1)
	v_add_f32_e32 v4, v4, v23
	s_waitcnt lgkmcnt(0)
	v_add_f32_e32 v3, v3, v24
	ds_bpermute_b32 v23, v25, v4
	ds_bpermute_b32 v24, v25, v3
	v_lshlrev_b32_e32 v25, 2, v31
	v_cndmask_b32_e32 v0, v0, v33, vcc
	v_lshlrev_b32_e32 v0, 2, v0
	s_waitcnt lgkmcnt(1)
	v_add_f32_e32 v4, v4, v23
	s_waitcnt lgkmcnt(0)
	v_add_f32_e32 v3, v3, v24
	ds_bpermute_b32 v23, v25, v4
	ds_bpermute_b32 v24, v25, v3
	v_lshl_add_u32 v25, v2, 4, s20
	s_waitcnt vmcnt(7)
	ds_write_b128 v25, v[6:9]
	s_waitcnt vmcnt(6)
	ds_write_b128 v25, v[10:13] offset:1024
	s_waitcnt vmcnt(5)
	ds_write_b128 v25, v[14:17] offset:2048
	s_waitcnt lgkmcnt(4)
	v_add_f32_e32 v4, v4, v23
	s_waitcnt lgkmcnt(3)
	v_add_f32_e32 v3, v3, v24
	ds_bpermute_b32 v23, v22, v4
	ds_bpermute_b32 v22, v22, v3
	s_and_b64 vcc, exec, s[94:95]
	s_waitcnt vmcnt(4)
	ds_write_b128 v25, v[18:21] offset:3072
	s_waitcnt lgkmcnt(2)
	v_add_f32_e32 v6, v4, v23
	s_waitcnt lgkmcnt(1)
	v_add_f32_e32 v3, v3, v22
	ds_bpermute_b32 v7, v0, v6
	ds_bpermute_b32 v4, v0, v3
	s_cbranch_vccnz .LBB0_745
	v_readlane_b32 s11, v255, 16
	s_bfe_u32 s11, s11, 0x20006
	v_lshrrev_b32_e32 v0, 4, v2
	v_lshl_or_b32 v0, s11, 2, v0
	v_and_b32_e32 v5, 15, v5
	s_lshl_b32 s12, s11, 10
	v_bitop3_b32 v5, v0, v5, 7 bitop3:0x6c
	v_lshlrev_b32_e32 v0, 8, v0
	s_add_i32 s14, s12, 0
	v_lshl_or_b32 v0, v5, 4, v0
	s_add_i32 m0, s14, 0x8000
	v_lshl_add_u64 v[8:9], s[8:9], 0, v[0:1]
	s_mov_b64 s[12:13], 0x1000
	global_load_lds_dwordx4 v0, s[8:9]
	v_lshl_add_u64 v[0:1], v[8:9], 0, s[12:13]
	s_add_i32 m0, s14, 0x9000
	s_mov_b64 s[12:13], 0x2000
	global_load_lds_dwordx4 v[0:1], off
	v_lshl_add_u64 v[0:1], v[8:9], 0, s[12:13]
	s_add_i32 m0, s14, 0xa000
	s_mov_b64 s[12:13], 0x3000
	global_load_lds_dwordx4 v[0:1], off
	v_lshl_add_u64 v[0:1], v[8:9], 0, s[12:13]
	s_add_i32 m0, s14, 0xb000
	s_nop 0
	global_load_lds_dwordx4 v[0:1], off
